# lru_carry: prefetch 16 steps of (P,E) pairs per trip, dependent FMA chain under a constant counted wait instead of vmcnt(0) per step
# speedup vs baseline: 1.0126x; 1.0126x over previous
; __device__ __forceinline__ int otid() { int t = __builtin_amdgcn_workitem_id_x(); asm volatile("" : "+v"(t)); return t; }
; __device__ __forceinline__ int obid() { int b = __builtin_amdgcn_workgroup_id_x(); asm volatile("" : "+s"(b)); return b; }
; __device__ __forceinline__ void lru_carry(const float* __restrict__ LSUM, float* __restrict__ LCAR) {
;     for (int id = obid() * 512 + otid(); id < 2048; id += gridDim.x * 512) {
;         const int b = id >> 10, g = (id >> 9) & 1, ch = id & 511; float c = 0.f;
;         for (int st = 0; st < 256; ++st) { const int seg = g ? 255 - st : st; const size_t ix = ((size_t)(b * 256 + seg) * 2 + g) * 512 + ch;
;             LCAR[ix] = c; c = LSUM[2 * ix] * c + LSUM[2 * ix + 1]; }
;     }
; }
.LBB0_503:
	v_readlane_b32 s2, v251, 10
	v_readlane_b32 s3, v251, 11
	s_add_i32 s7, s5, 7
	s_mov_b32 s6, s4
	v_mov_b32_e32 v4, s7
	v_mov_b32_e32 v5, s6
	v_cndmask_b32_e32 v4, v4, v5, vcc
	v_or_b32_e32 v4, v4, v3
	v_ashrrev_i32_e32 v5, 31, v4
	v_lshlrev_b64 v[4:5], 10, v[4:5]
	v_or_b32_e32 v4, v4, v2
	v_lshl_add_u64 v[42:43], v[4:5], 2, s[2:3]
	v_lshl_add_u64 v[4:5], v[4:5], 3, s[30:31]
	global_load_dwordx2 v[10:11], v[4:5], off
	s_add_i32 s6, s6, 1
	s_add_i32 s7, s7, -1
	v_mov_b32_e32 v4, s7
	v_mov_b32_e32 v5, s6
	v_cndmask_b32_e32 v4, v4, v5, vcc
	v_or_b32_e32 v4, v4, v3
	v_ashrrev_i32_e32 v5, 31, v4
	v_lshlrev_b64 v[4:5], 10, v[4:5]
	v_or_b32_e32 v4, v4, v2
	v_lshl_add_u64 v[44:45], v[4:5], 2, s[2:3]
	v_lshl_add_u64 v[4:5], v[4:5], 3, s[30:31]
	global_load_dwordx2 v[12:13], v[4:5], off
	s_add_i32 s6, s6, 1
	s_add_i32 s7, s7, -1
	v_mov_b32_e32 v4, s7
	v_mov_b32_e32 v5, s6
	v_cndmask_b32_e32 v4, v4, v5, vcc
	v_or_b32_e32 v4, v4, v3
	v_ashrrev_i32_e32 v5, 31, v4
	v_lshlrev_b64 v[4:5], 10, v[4:5]
	v_or_b32_e32 v4, v4, v2
	v_lshl_add_u64 v[46:47], v[4:5], 2, s[2:3]
	v_lshl_add_u64 v[4:5], v[4:5], 3, s[30:31]
	global_load_dwordx2 v[14:15], v[4:5], off
	s_add_i32 s6, s6, 1
	s_add_i32 s7, s7, -1
	v_mov_b32_e32 v4, s7
	v_mov_b32_e32 v5, s6
	v_cndmask_b32_e32 v4, v4, v5, vcc
	v_or_b32_e32 v4, v4, v3
	v_ashrrev_i32_e32 v5, 31, v4
	v_lshlrev_b64 v[4:5], 10, v[4:5]
	v_or_b32_e32 v4, v4, v2
	v_lshl_add_u64 v[48:49], v[4:5], 2, s[2:3]
	v_lshl_add_u64 v[4:5], v[4:5], 3, s[30:31]
	global_load_dwordx2 v[16:17], v[4:5], off
	s_add_i32 s6, s6, 1
	s_add_i32 s7, s7, -1
	v_mov_b32_e32 v4, s7
	v_mov_b32_e32 v5, s6
	v_cndmask_b32_e32 v4, v4, v5, vcc
	v_or_b32_e32 v4, v4, v3
	v_ashrrev_i32_e32 v5, 31, v4
	v_lshlrev_b64 v[4:5], 10, v[4:5]
	v_or_b32_e32 v4, v4, v2
	v_lshl_add_u64 v[50:51], v[4:5], 2, s[2:3]
	v_lshl_add_u64 v[4:5], v[4:5], 3, s[30:31]
	global_load_dwordx2 v[18:19], v[4:5], off
	s_add_i32 s6, s6, 1
	s_add_i32 s7, s7, -1
	v_mov_b32_e32 v4, s7
	v_mov_b32_e32 v5, s6
	v_cndmask_b32_e32 v4, v4, v5, vcc
	v_or_b32_e32 v4, v4, v3
	v_ashrrev_i32_e32 v5, 31, v4
	v_lshlrev_b64 v[4:5], 10, v[4:5]
	v_or_b32_e32 v4, v4, v2
	v_lshl_add_u64 v[52:53], v[4:5], 2, s[2:3]
	v_lshl_add_u64 v[4:5], v[4:5], 3, s[30:31]
	global_load_dwordx2 v[20:21], v[4:5], off
	s_add_i32 s6, s6, 1
	s_add_i32 s7, s7, -1
	v_mov_b32_e32 v4, s7
	v_mov_b32_e32 v5, s6
	v_cndmask_b32_e32 v4, v4, v5, vcc
	v_or_b32_e32 v4, v4, v3
	v_ashrrev_i32_e32 v5, 31, v4
	v_lshlrev_b64 v[4:5], 10, v[4:5]
	v_or_b32_e32 v4, v4, v2
	v_lshl_add_u64 v[54:55], v[4:5], 2, s[2:3]
	v_lshl_add_u64 v[4:5], v[4:5], 3, s[30:31]
	global_load_dwordx2 v[22:23], v[4:5], off
	s_add_i32 s6, s6, 1
	s_add_i32 s7, s7, -1
	v_mov_b32_e32 v4, s7
	v_mov_b32_e32 v5, s6
	v_cndmask_b32_e32 v4, v4, v5, vcc
	v_or_b32_e32 v4, v4, v3
	v_ashrrev_i32_e32 v5, 31, v4
	v_lshlrev_b64 v[4:5], 10, v[4:5]
	v_or_b32_e32 v4, v4, v2
	v_lshl_add_u64 v[56:57], v[4:5], 2, s[2:3]
	v_lshl_add_u64 v[4:5], v[4:5], 3, s[30:31]
	global_load_dwordx2 v[24:25], v[4:5], off
	s_add_i32 s6, s6, 1
	s_add_i32 s7, s7, -1
	v_mov_b32_e32 v4, s7
	v_mov_b32_e32 v5, s6
	v_cndmask_b32_e32 v4, v4, v5, vcc
	v_or_b32_e32 v4, v4, v3
	v_ashrrev_i32_e32 v5, 31, v4
	v_lshlrev_b64 v[4:5], 10, v[4:5]
	v_or_b32_e32 v4, v4, v2
	v_lshl_add_u64 v[58:59], v[4:5], 2, s[2:3]
	v_lshl_add_u64 v[4:5], v[4:5], 3, s[30:31]
	global_load_dwordx2 v[26:27], v[4:5], off
	s_add_i32 s6, s6, 1
	s_add_i32 s7, s7, -1
	v_mov_b32_e32 v4, s7
	v_mov_b32_e32 v5, s6
	v_cndmask_b32_e32 v4, v4, v5, vcc
	v_or_b32_e32 v4, v4, v3
	v_ashrrev_i32_e32 v5, 31, v4
	v_lshlrev_b64 v[4:5], 10, v[4:5]
	v_or_b32_e32 v4, v4, v2
	v_lshl_add_u64 v[60:61], v[4:5], 2, s[2:3]
	v_lshl_add_u64 v[4:5], v[4:5], 3, s[30:31]
	global_load_dwordx2 v[28:29], v[4:5], off
	s_add_i32 s6, s6, 1
	s_add_i32 s7, s7, -1
	v_mov_b32_e32 v4, s7
	v_mov_b32_e32 v5, s6
	v_cndmask_b32_e32 v4, v4, v5, vcc
	v_or_b32_e32 v4, v4, v3
	v_ashrrev_i32_e32 v5, 31, v4
	v_lshlrev_b64 v[4:5], 10, v[4:5]
	v_or_b32_e32 v4, v4, v2
	v_lshl_add_u64 v[62:63], v[4:5], 2, s[2:3]
	v_lshl_add_u64 v[4:5], v[4:5], 3, s[30:31]
	global_load_dwordx2 v[30:31], v[4:5], off
	s_add_i32 s6, s6, 1
	s_add_i32 s7, s7, -1
	v_mov_b32_e32 v4, s7
	v_mov_b32_e32 v5, s6
	v_cndmask_b32_e32 v4, v4, v5, vcc
	v_or_b32_e32 v4, v4, v3
	v_ashrrev_i32_e32 v5, 31, v4
	v_lshlrev_b64 v[4:5], 10, v[4:5]
	v_or_b32_e32 v4, v4, v2
	v_lshl_add_u64 v[64:65], v[4:5], 2, s[2:3]
	v_lshl_add_u64 v[4:5], v[4:5], 3, s[30:31]
	global_load_dwordx2 v[32:33], v[4:5], off
	s_add_i32 s6, s6, 1
	s_add_i32 s7, s7, -1
	v_mov_b32_e32 v4, s7
	v_mov_b32_e32 v5, s6
	v_cndmask_b32_e32 v4, v4, v5, vcc
	v_or_b32_e32 v4, v4, v3
	v_ashrrev_i32_e32 v5, 31, v4
	v_lshlrev_b64 v[4:5], 10, v[4:5]
	v_or_b32_e32 v4, v4, v2
	v_lshl_add_u64 v[66:67], v[4:5], 2, s[2:3]
	v_lshl_add_u64 v[4:5], v[4:5], 3, s[30:31]
	global_load_dwordx2 v[34:35], v[4:5], off
	s_add_i32 s6, s6, 1
	s_add_i32 s7, s7, -1
	v_mov_b32_e32 v4, s7
	v_mov_b32_e32 v5, s6
	v_cndmask_b32_e32 v4, v4, v5, vcc
	v_or_b32_e32 v4, v4, v3
	v_ashrrev_i32_e32 v5, 31, v4
	v_lshlrev_b64 v[4:5], 10, v[4:5]
	v_or_b32_e32 v4, v4, v2
	v_lshl_add_u64 v[68:69], v[4:5], 2, s[2:3]
	v_lshl_add_u64 v[4:5], v[4:5], 3, s[30:31]
	global_load_dwordx2 v[36:37], v[4:5], off
	s_add_i32 s6, s6, 1
	s_add_i32 s7, s7, -1
	v_mov_b32_e32 v4, s7
	v_mov_b32_e32 v5, s6
	v_cndmask_b32_e32 v4, v4, v5, vcc
	v_or_b32_e32 v4, v4, v3
	v_ashrrev_i32_e32 v5, 31, v4
	v_lshlrev_b64 v[4:5], 10, v[4:5]
	v_or_b32_e32 v4, v4, v2
	v_lshl_add_u64 v[70:71], v[4:5], 2, s[2:3]
	v_lshl_add_u64 v[4:5], v[4:5], 3, s[30:31]
	global_load_dwordx2 v[38:39], v[4:5], off
	s_add_i32 s6, s6, 1
	s_add_i32 s7, s7, -1
	v_mov_b32_e32 v4, s7
	v_mov_b32_e32 v5, s6
	v_cndmask_b32_e32 v4, v4, v5, vcc
	v_or_b32_e32 v4, v4, v3
	v_ashrrev_i32_e32 v5, 31, v4
	v_lshlrev_b64 v[4:5], 10, v[4:5]
	v_or_b32_e32 v4, v4, v2
	v_lshl_add_u64 v[72:73], v[4:5], 2, s[2:3]
	v_lshl_add_u64 v[4:5], v[4:5], 3, s[30:31]
	global_load_dwordx2 v[40:41], v[4:5], off
	global_store_dword v[42:43], v7, off
	s_waitcnt vmcnt(16)
; __device__ __forceinline__ void lru_carry(const float* __restrict__ LSUM, float* __restrict__ LCAR) {
;     ...
;         for (int st = 0; st < 256; ++st) { const int seg = g ? 255 - st : st; const size_t ix = ((size_t)(b * 256 + seg) * 2 + g) * 512 + ch;
;             LCAR[ix] = c; c = LSUM[2 * ix] * c + LSUM[2 * ix + 1]; }
	v_fmac_f32_e32 v11, v7, v10
	global_store_dword v[44:45], v11, off
	s_waitcnt vmcnt(16)
	v_fmac_f32_e32 v13, v11, v12
	global_store_dword v[46:47], v13, off
	s_waitcnt vmcnt(16)
	v_fmac_f32_e32 v15, v13, v14
	global_store_dword v[48:49], v15, off
	s_waitcnt vmcnt(16)
	v_fmac_f32_e32 v17, v15, v16
	global_store_dword v[50:51], v17, off
	s_waitcnt vmcnt(16)
	v_fmac_f32_e32 v19, v17, v18
	global_store_dword v[52:53], v19, off
	s_waitcnt vmcnt(16)
	v_fmac_f32_e32 v21, v19, v20
	global_store_dword v[54:55], v21, off
	s_waitcnt vmcnt(16)
	v_fmac_f32_e32 v23, v21, v22
	global_store_dword v[56:57], v23, off
	s_waitcnt vmcnt(16)
	v_fmac_f32_e32 v25, v23, v24
	global_store_dword v[58:59], v25, off
	s_waitcnt vmcnt(16)
	v_fmac_f32_e32 v27, v25, v26
	global_store_dword v[60:61], v27, off
	s_waitcnt vmcnt(16)
	v_fmac_f32_e32 v29, v27, v28
	global_store_dword v[62:63], v29, off
	s_waitcnt vmcnt(16)
	v_fmac_f32_e32 v31, v29, v30
	global_store_dword v[64:65], v31, off
	s_waitcnt vmcnt(16)
	v_fmac_f32_e32 v33, v31, v32
	global_store_dword v[66:67], v33, off
	s_waitcnt vmcnt(16)
	v_fmac_f32_e32 v35, v33, v34
	global_store_dword v[68:69], v35, off
	s_waitcnt vmcnt(16)
	v_fmac_f32_e32 v37, v35, v36
	global_store_dword v[70:71], v37, off
	s_waitcnt vmcnt(16)
	v_fmac_f32_e32 v39, v37, v38
	global_store_dword v[72:73], v39, off
	s_waitcnt vmcnt(16)
	v_fmac_f32_e32 v41, v39, v40
	v_mov_b32_e32 v7, v41
	s_add_i32 s4, s4, 16
	s_add_i32 s5, s5, -16
	s_cmpk_eq_i32 s4, 0x100
	s_cbranch_scc0 .LBB0_503
	s_waitcnt vmcnt(0)
	v_readlane_b32 s2, v251, 43
	s_nop 1
	v_add_u32_e32 v1, s2, v1
	v_cmp_lt_i32_e32 vcc, s14, v1
	s_or_b64 s[24:25], vcc, s[24:25]
	s_andn2_b64 exec, exec, s[24:25]
	s_cbranch_execnz .LBB0_502
